# v042 plus select find_bin suffix scans by DPP (row_shr/row_bcast prefix scan + readlane total) instead of six ds_bpermute chains
# speedup vs baseline: 1.0056x; 1.0056x over previous
; #define LAS __attribute__((address_space(3)))
; __device__ __forceinline__ unsigned suffix_incl(unsigned v, int lane) {
; #pragma unroll
;     for (int off = 1; off < 64; off <<= 1) { const unsigned o = __shfl_down(v, off); if (lane + off < 64) v += o; }
;     return v;
; }
; template <int BITS> __device__ __forceinline__ unsigned find_bin(const LAS unsigned* hist, unsigned& k, int lane) {
;     constexpr int NBIN = 1 << BITS, PER = NBIN / 64;
;     unsigned s = 0;
; #pragma unroll 8
;     for (int j = 0; j < PER; ++j) s += hist[PER * lane + ((j + lane) & (PER - 1))];
;     const unsigned incl = suffix_incl(s, lane), excl = incl - s;
;     const bool hit = (excl < k) && (k <= incl);
;     const int Ls = __ffsll((unsigned long long)__ballot(hit)) - 1;
;     const unsigned exclS = __shfl(excl, Ls);
;     const unsigned h = (lane < PER) ? hist[PER * Ls + (lane & (PER - 1))] : 0u;
;     const unsigned incl2 = suffix_incl(h, lane) + exclS, excl2 = incl2 - h;
;     const bool hit2 = (lane < PER) && (excl2 < k) && (k <= incl2);
;     const int js = __ffsll((unsigned long long)__ballot(hit2)) - 1;
;     k -= __shfl(excl2, js);
;     return (unsigned)(PER * Ls + js);
; }
.LBB0_749:
	s_or_b64 exec, exec, s[0:1]
	v_and_b32_e32 v3, 63, v226
	v_cmp_ne_u32_e32 vcc, 63, v3
	v_lshl_or_b32 v70, v226, 2, v230
	v_and_b32_e32 v71, 64, v226
	v_addc_co_u32_e32 v0, vcc, 0, v226, vcc
	v_lshlrev_b32_e32 v0, 2, v0
	v_cmp_gt_u32_e32 vcc, 62, v3
	s_mov_b32 s24, 0
	s_nop 1
	v_cndmask_b32_e64 v5, 0, 2, vcc
	v_add_lshl_u32 v66, v5, v226, 2
	v_cmp_gt_u32_e32 vcc, 60, v3
	s_nop 1
	v_cndmask_b32_e64 v6, 0, 4, vcc
	v_add_lshl_u32 v67, v6, v226, 2
	v_cmp_gt_u32_e32 vcc, 56, v3
	s_nop 1
	v_cndmask_b32_e64 v6, 0, 8, vcc
	v_add_lshl_u32 v68, v6, v226, 2
	v_cmp_gt_u32_e32 vcc, 48, v3
	s_nop 1
	v_cndmask_b32_e64 v3, 0, 16, vcc
	v_add_lshl_u32 v69, v3, v226, 2
	v_mov_b32_e32 v4, v2
	s_nop 1
	v_add_u32_dpp v4, v4, v4 row_shr:1 row_mask:0xf bank_mask:0xf
	s_nop 1
	v_add_u32_dpp v4, v4, v4 row_shr:2 row_mask:0xf bank_mask:0xf
	s_nop 1
	v_add_u32_dpp v4, v4, v4 row_shr:4 row_mask:0xf bank_mask:0xf
	s_nop 1
	v_add_u32_dpp v4, v4, v4 row_shr:8 row_mask:0xf bank_mask:0xf
	s_nop 1
	v_add_u32_dpp v4, v4, v4 row_bcast:15 row_mask:0xa bank_mask:0xf
	s_nop 1
	v_add_u32_dpp v4, v4, v4 row_bcast:31 row_mask:0xc bank_mask:0xf
	s_nop 1
	v_readlane_b32 s1, v4, 63
	s_nop 1
	v_sub_u32_e32 v3, s1, v4
	v_add_u32_e32 v3, v3, v2
	s_movk_i32 s0, 0xff
	v_sub_u32_e32 v2, v3, v2
	v_cmp_lt_u32_e32 vcc, s0, v3
	v_cmp_gt_u32_e64 s[0:1], s54, v2
	s_and_b64 s[0:1], vcc, s[0:1]
	s_nop 0
	v_cndmask_b32_e64 v3, 0, 1, s[0:1]
	v_cmp_ne_u32_e32 vcc, 0, v3
	s_ff1_i32_b64 s0, vcc
	s_cmp_lg_u64 vcc, 0
	s_cselect_b32 s4, s0, -1
	v_and_or_b32 v3, s4, 63, v71
	v_lshlrev_b32_e32 v3, 2, v3
	ds_bpermute_b32 v2, v3, v2
	v_mov_b32_e32 v3, 0
	s_mov_b64 s[0:1], exec
	v_readlane_b32 s6, v248, 36
	v_readlane_b32 s7, v248, 37
	s_and_b64 s[6:7], s[0:1], s[6:7]
	s_mov_b64 exec, s[6:7]
	v_lshl_add_u32 v3, s4, 8, v135
	ds_read_b32 v3, v3
	s_or_b64 exec, exec, s[0:1]
	s_waitcnt lgkmcnt(0)
	v_readlane_b32 s6, v248, 36
	v_readlane_b32 s7, v248, 37
	s_mov_b32 s39, 0
	s_mov_b32 s38, 0
	v_mov_b32_e32 v5, v3
	s_nop 1
	v_add_u32_dpp v5, v5, v5 row_shr:1 row_mask:0xf bank_mask:0xf
	s_nop 1
	v_add_u32_dpp v5, v5, v5 row_shr:2 row_mask:0xf bank_mask:0xf
	s_nop 1
	v_add_u32_dpp v5, v5, v5 row_shr:4 row_mask:0xf bank_mask:0xf
	s_nop 1
	v_add_u32_dpp v5, v5, v5 row_shr:8 row_mask:0xf bank_mask:0xf
	s_nop 1
	v_add_u32_dpp v5, v5, v5 row_bcast:15 row_mask:0xa bank_mask:0xf
	s_nop 1
	v_add_u32_dpp v5, v5, v5 row_bcast:31 row_mask:0xc bank_mask:0xf
	s_nop 1
	v_readlane_b32 s1, v5, 63
	s_nop 1
	v_sub_u32_e32 v4, s1, v5
	v_add_u32_e32 v4, v4, v3
	s_movk_i32 s0, 0xff
	v_add_u32_e32 v2, v4, v2
	v_sub_u32_e32 v72, v2, v3
	v_cmp_gt_u32_e32 vcc, s54, v72
	v_cmp_lt_u32_e64 s[0:1], s0, v2
	s_and_b64 s[0:1], s[0:1], vcc
	s_and_b64 s[0:1], s[6:7], s[0:1]
	v_cndmask_b32_e64 v2, 0, 1, s[0:1]
	v_cmp_ne_u32_e32 vcc, 0, v2
	s_ff1_i32_b64 s0, vcc
	s_cmp_lg_u64 vcc, 0
	s_cselect_b32 s58, s0, -1
	s_lshl_b32 s0, s4, 6
	s_add_i32 s73, s58, s0
	s_branch .LBB0_753

; #define LAS __attribute__((address_space(3)))
; __device__ __forceinline__ unsigned suffix_incl(unsigned v, int lane) {
; #pragma unroll
;     for (int off = 1; off < 64; off <<= 1) { const unsigned o = __shfl_down(v, off); if (lane + off < 64) v += o; }
;     return v;
; }
; template <int BITS> __device__ __forceinline__ unsigned find_bin(const LAS unsigned* hist, unsigned& k, int lane) {
;     constexpr int NBIN = 1 << BITS, PER = NBIN / 64;
;     unsigned s = 0;
; #pragma unroll 8
;     for (int j = 0; j < PER; ++j) s += hist[PER * lane + ((j + lane) & (PER - 1))];
;     const unsigned incl = suffix_incl(s, lane), excl = incl - s;
;     const bool hit = (excl < k) && (k <= incl);
;     const int Ls = __ffsll((unsigned long long)__ballot(hit)) - 1;
;     const unsigned exclS = __shfl(excl, Ls);
;     const unsigned h = (lane < PER) ? hist[PER * Ls + (lane & (PER - 1))] : 0u;
;     const unsigned incl2 = suffix_incl(h, lane) + exclS, excl2 = incl2 - h;
;     const bool hit2 = (lane < PER) && (excl2 < k) && (k <= incl2);
;     const int js = __ffsll((unsigned long long)__ballot(hit2)) - 1;
;     k -= __shfl(excl2, js);
;     return (unsigned)(PER * Ls + js);
; }
.LBB0_1234:
	s_or_b64 exec, exec, s[0:1]
	s_waitcnt lgkmcnt(0)
	v_mov_b32_e32 v5, v3
	s_nop 1
	v_add_u32_dpp v5, v5, v5 row_shr:1 row_mask:0xf bank_mask:0xf
	s_nop 1
	v_add_u32_dpp v5, v5, v5 row_shr:2 row_mask:0xf bank_mask:0xf
	s_nop 1
	v_add_u32_dpp v5, v5, v5 row_shr:4 row_mask:0xf bank_mask:0xf
	s_nop 1
	v_add_u32_dpp v5, v5, v5 row_shr:8 row_mask:0xf bank_mask:0xf
	s_nop 1
	v_add_u32_dpp v5, v5, v5 row_bcast:15 row_mask:0xa bank_mask:0xf
	s_nop 1
	v_add_u32_dpp v5, v5, v5 row_bcast:31 row_mask:0xc bank_mask:0xf
	s_nop 1
	v_readlane_b32 s1, v5, 63
	s_nop 1
	v_sub_u32_e32 v4, s1, v5
	v_add_u32_e32 v4, v4, v3
	v_sub_u32_e32 v2, 0x100, v6
	v_sub_u32_e32 v3, v4, v3
	v_cmp_le_u32_e64 s[0:1], v2, v4
	v_cmp_lt_u32_e64 s[4:5], v3, v2
	s_and_b64 s[0:1], s[0:1], s[4:5]
	v_cndmask_b32_e64 v4, 0, 1, s[0:1]
	v_cmp_ne_u32_e64 s[0:1], 0, v4
	s_ff1_i32_b64 s4, s[0:1]
	s_cmp_lg_u64 s[0:1], 0
	s_cselect_b32 s8, s4, -1
	v_and_or_b32 v4, s8, 63, v71
	v_lshlrev_b32_e32 v4, 2, v4
	ds_bpermute_b32 v3, v4, v3
	v_mov_b32_e32 v4, 0
	s_mov_b64 s[0:1], exec
	v_readlane_b32 s4, v248, 40
	v_readlane_b32 s5, v248, 41
	s_and_b64 s[4:5], s[0:1], s[4:5]
	s_mov_b64 exec, s[4:5]
	v_lshl_add_u32 v4, s8, 6, v111
	ds_read_b32 v4, v4 offset:8192
	s_or_b64 exec, exec, s[0:1]
	s_waitcnt lgkmcnt(0)
	v_mov_b32_e32 v6, v4
	s_nop 1
	v_add_u32_dpp v6, v6, v6 row_shr:1 row_mask:0xf bank_mask:0xf
	s_nop 1
	v_add_u32_dpp v6, v6, v6 row_shr:2 row_mask:0xf bank_mask:0xf
	s_nop 1
	v_add_u32_dpp v6, v6, v6 row_shr:4 row_mask:0xf bank_mask:0xf
	s_nop 1
	v_add_u32_dpp v6, v6, v6 row_shr:8 row_mask:0xf bank_mask:0xf
	s_nop 1
	v_add_u32_dpp v6, v6, v6 row_bcast:15 row_mask:0xa bank_mask:0xf
	s_nop 1
	v_add_u32_dpp v6, v6, v6 row_bcast:31 row_mask:0xc bank_mask:0xf
	s_nop 1
	v_readlane_b32 s1, v6, 63
	s_nop 1
	v_sub_u32_e32 v5, s1, v6
	v_add_u32_e32 v5, v5, v4
	v_add_u32_e32 v3, v5, v3
	v_sub_u32_e32 v4, v3, v4
	v_cmp_le_u32_e64 s[0:1], v2, v3
	v_cmp_lt_u32_e64 s[4:5], v4, v2
	s_and_b64 s[0:1], s[0:1], s[4:5]
	v_readlane_b32 s4, v248, 40
	v_readlane_b32 s5, v248, 41
	s_and_b64 s[0:1], s[4:5], s[0:1]
	v_cndmask_b32_e64 v3, 0, 1, s[0:1]
	v_cmp_ne_u32_e64 s[0:1], 0, v3
	s_ff1_i32_b64 s4, s[0:1]
	s_cmp_lg_u64 s[0:1], 0
	s_cselect_b32 s9, s4, -1
	v_and_or_b32 v3, s9, 63, v71
	v_lshlrev_b32_e32 v3, 2, v3
	ds_bpermute_b32 v3, v3, v4
	s_mov_b64 s[4:5], exec
	v_readlane_b32 s0, v248, 38
	v_readlane_b32 s1, v248, 39
	s_and_b64 s[0:1], s[4:5], s[0:1]
	s_movk_i32 s10, 0x2ff
	s_mov_b64 exec, s[0:1]
	s_cbranch_execz .LBB0_1239
	s_mov_b64 s[6:7], 0
	v_mov_b32_e32 v4, v143
	v_mov_b32_e32 v5, v145

; #define LAS __attribute__((address_space(3)))
; __device__ __forceinline__ unsigned suffix_incl(unsigned v, int lane) {
; #pragma unroll
;     for (int off = 1; off < 64; off <<= 1) { const unsigned o = __shfl_down(v, off); if (lane + off < 64) v += o; }
;     return v;
; }
; template <int BITS> __device__ __forceinline__ unsigned find_bin(const LAS unsigned* hist, unsigned& k, int lane) {
;     constexpr int NBIN = 1 << BITS, PER = NBIN / 64;
;     unsigned s = 0;
; #pragma unroll 8
;     for (int j = 0; j < PER; ++j) s += hist[PER * lane + ((j + lane) & (PER - 1))];
;     const unsigned incl = suffix_incl(s, lane), excl = incl - s;
;     const bool hit = (excl < k) && (k <= incl);
;     const int Ls = __ffsll((unsigned long long)__ballot(hit)) - 1;
;     const unsigned exclS = __shfl(excl, Ls);
;     const unsigned h = (lane < PER) ? hist[PER * Ls + (lane & (PER - 1))] : 0u;
;     const unsigned incl2 = suffix_incl(h, lane) + exclS, excl2 = incl2 - h;
;     const bool hit2 = (lane < PER) && (excl2 < k) && (k <= incl2);
;     const int js = __ffsll((unsigned long long)__ballot(hit2)) - 1;
;     k -= __shfl(excl2, js);
;     return (unsigned)(PER * Ls + js);
; }
.LBB0_1249:
	s_or_b64 exec, exec, s[0:1]
	s_waitcnt lgkmcnt(0)
	v_sub_u32_e32 v2, v2, v3
	v_mov_b32_e32 v5, v4
	s_nop 1
	v_add_u32_dpp v5, v5, v5 row_shr:1 row_mask:0xf bank_mask:0xf
	s_nop 1
	v_add_u32_dpp v5, v5, v5 row_shr:2 row_mask:0xf bank_mask:0xf
	s_nop 1
	v_add_u32_dpp v5, v5, v5 row_shr:4 row_mask:0xf bank_mask:0xf
	s_nop 1
	v_add_u32_dpp v5, v5, v5 row_shr:8 row_mask:0xf bank_mask:0xf
	s_nop 1
	v_add_u32_dpp v5, v5, v5 row_bcast:15 row_mask:0xa bank_mask:0xf
	s_nop 1
	v_add_u32_dpp v5, v5, v5 row_bcast:31 row_mask:0xc bank_mask:0xf
	s_nop 1
	v_readlane_b32 s1, v5, 63
	s_nop 1
	v_sub_u32_e32 v3, s1, v5
	v_add_u32_e32 v3, v3, v4
	v_sub_u32_e32 v4, v3, v4
	v_cmp_le_u32_e32 vcc, v2, v3
	v_cmp_lt_u32_e64 s[0:1], v4, v2
	s_and_b64 s[0:1], vcc, s[0:1]
	s_nop 0
	v_cndmask_b32_e64 v3, 0, 1, s[0:1]
	v_cmp_ne_u32_e32 vcc, 0, v3
	s_ff1_i32_b64 s0, vcc
	s_cmp_lg_u64 vcc, 0
	s_cselect_b32 s4, s0, -1
	v_and_or_b32 v3, s4, 63, v71
	v_lshlrev_b32_e32 v3, 2, v3
	ds_bpermute_b32 v3, v3, v4
	v_mov_b32_e32 v4, 0
	s_mov_b64 s[0:1], exec
	v_readlane_b32 s6, v248, 40
	v_readlane_b32 s7, v248, 41
	s_and_b64 s[6:7], s[0:1], s[6:7]
	s_mov_b64 exec, s[6:7]
	v_lshl_add_u32 v4, s4, 6, v111
	ds_read_b32 v4, v4 offset:8192
	s_or_b64 exec, exec, s[0:1]
	s_waitcnt lgkmcnt(0)
	v_readlane_b32 s6, v248, 40
	v_readlane_b32 s7, v248, 41
	v_mov_b32_e32 v5, v4
	s_nop 1
	v_add_u32_dpp v5, v5, v5 row_shr:1 row_mask:0xf bank_mask:0xf
	s_nop 1
	v_add_u32_dpp v5, v5, v5 row_shr:2 row_mask:0xf bank_mask:0xf
	s_nop 1
	v_add_u32_dpp v5, v5, v5 row_shr:4 row_mask:0xf bank_mask:0xf
	s_nop 1
	v_add_u32_dpp v5, v5, v5 row_shr:8 row_mask:0xf bank_mask:0xf
	s_nop 1
	v_add_u32_dpp v5, v5, v5 row_bcast:15 row_mask:0xa bank_mask:0xf
	s_nop 1
	v_add_u32_dpp v5, v5, v5 row_bcast:31 row_mask:0xc bank_mask:0xf
	s_nop 1
	v_readlane_b32 s1, v5, 63
	s_nop 1
	v_sub_u32_e32 v0, s1, v5
	v_add_u32_e32 v0, v0, v4
	v_add_u32_e32 v0, v0, v3
	v_sub_u32_e32 v3, v0, v4
	v_cmp_le_u32_e32 vcc, v2, v0
	v_cmp_lt_u32_e64 s[0:1], v3, v2
	s_and_b64 s[0:1], vcc, s[0:1]
	s_and_b64 s[0:1], s[6:7], s[0:1]
	v_cndmask_b32_e64 v0, 0, 1, s[0:1]
	v_cmp_ne_u32_e32 vcc, 0, v0
	s_ff1_i32_b64 s0, vcc
	s_cmp_lg_u64 vcc, 0
	s_cselect_b32 s0, s0, -1
	v_and_or_b32 v0, s0, 63, v71
	v_lshlrev_b32_e32 v0, 2, v0
	ds_bpermute_b32 v0, v0, v3
	s_cmp_eq_u32 s39, 0
	s_cbranch_scc1 .LBB0_1266
	s_lshl_b32 s1, s4, 4
	s_add_i32 s0, s0, s1
	s_lshl_b32 s1, s8, 10
	s_or_b32 s25, s0, s1
	s_lshl_b32 s0, s0, 2
	s_add_i32 s0, s33, s0
	s_waitcnt lgkmcnt(0)
	v_sub_u32_e32 v0, v2, v0
	v_mov_b32_e32 v2, s0
	ds_read_b32 v2, v2 offset:8192
	s_mov_b32 s30, 0
	s_waitcnt lgkmcnt(0)
	v_cmp_ne_u32_e64 s[0:1], v2, v0
	s_branch .LBB0_1254
